# attention fixedref loop: relax 3 lgkmcnt over-waits caused by inline-asm V reads (K frags are older than the V reads)
# speedup vs baseline: 1.0064x; 1.0064x over previous
.LBB0_199:
	v_pk_add_f32 v[94:95], v[94:95], 0 op_sel_hi:[1,0]
	s_waitcnt lgkmcnt(3)
	v_mfma_f32_32x32x16_bf16 v[32:47], v[86:89], v[70:73], v[32:47]
	v_add_f32_e64 v94, v96, v94
	v_add_f32_e64 v95, v97, v95
	s_add_i32 s8, s7, 1
	v_add_f32_e64 v94, v98, v94
	v_add_f32_e64 v95, v99, v95
	s_cmp_eq_u32 s7, s43
	v_pk_add_f32 v[94:95], v[100:101], v[94:95]
	s_cselect_b32 s58, s42, s8
	v_pk_add_f32 v[94:95], v[102:103], v[94:95]
	s_waitcnt lgkmcnt(2)
	v_mfma_f32_32x32x16_bf16 v[48:63], v[82:85], v[70:73], v[48:63]
	v_add_f32_e64 v94, v104, v94
	v_add_f32_e64 v95, v105, v95
	s_add_i32 s7, s6, 1
	v_add_f32_e64 v94, v106, v94
	v_add_f32_e64 v95, v107, v95
	s_cmp_eq_u32 s6, s43
	v_pk_add_f32 v[94:95], v[108:109], v[94:95]
	s_cselect_b32 s59, s42, s7
	v_pk_add_f32 v[94:95], v[122:123], v[94:95]
	s_waitcnt lgkmcnt(1)
	v_mfma_f32_32x32x16_bf16 v[32:47], v[78:81], v[66:69], v[32:47]
	v_add_f32_e64 v94, v124, v94
	v_add_f32_e64 v95, v125, v95
	v_add_f32_e64 v94, v126, v94
	v_add_f32_e64 v95, v127, v95
	v_add_f32_e64 v94, v128, v94
	v_add_f32_e64 v95, v129, v95
	s_nop 5
	v_exp_f32_e32 v32, v32
	v_pk_add_f32 v[94:95], v[130:131], v[94:95]
	v_add_u32_e32 v130, 0x2000, v139
	ds_read_b64_tr_b16 v[82:83], v130 offset:0
	v_pk_add_f32 v[94:95], v[132:133], v[94:95]
	ds_read_b64_tr_b16 v[84:85], v130 offset:512
	ds_read_b64_tr_b16 v[86:87], v130 offset:4096
	ds_read_b64_tr_b16 v[88:89], v130 offset:4608
	v_exp_f32_e32 v33, v33
	v_pk_add_f32 v[94:95], v[134:135], v[94:95]
	v_exp_f32_e32 v34, v34
	v_pk_add_f32 v[94:95], v[136:137], v[94:95]
	v_exp_f32_e32 v35, v35
	v_add_f32_e32 v91, v94, v95
	ds_read_b64_tr_b16 v[94:95], v130 offset:1024
	ds_read_b64_tr_b16 v[96:97], v130 offset:1536
	ds_read_b64_tr_b16 v[98:99], v130 offset:5120
	ds_read_b64_tr_b16 v[100:101], v130 offset:5632
	ds_read_b64_tr_b16 v[102:103], v130 offset:2048
	ds_read_b64_tr_b16 v[104:105], v130 offset:2560
	ds_read_b64_tr_b16 v[106:107], v130 offset:6144
	ds_read_b64_tr_b16 v[108:109], v130 offset:6656
	ds_read_b64_tr_b16 v[122:123], v130 offset:3072
	ds_read_b64_tr_b16 v[124:125], v130 offset:3584
	ds_read_b64_tr_b16 v[126:127], v130 offset:7168
	v_exp_f32_e32 v36, v36
	v_exp_f32_e32 v37, v37
	ds_read_b64_tr_b16 v[128:129], v130 offset:7680
	v_exp_f32_e32 v38, v38
	v_exp_f32_e32 v39, v39
	v_pk_add_f32 v[78:79], v[32:33], 0 op_sel_hi:[1,0]
	s_waitcnt lgkmcnt(12)
	v_add_f32_e32 v91, v157, v91
	v_pk_add_f32 v[78:79], v[34:35], v[78:79]
	v_cvt_pk_bf16_f32 v32, v32, v33
	v_pk_add_f32 v[78:79], v[36:37], v[78:79]
	v_cvt_pk_bf16_f32 v33, v34, v35
	v_pk_add_f32 v[78:79], v[38:39], v[78:79]
	v_cvt_pk_bf16_f32 v34, v36, v37
	v_cvt_pk_bf16_f32 v35, v38, v39
	s_nop 1
	v_mfma_f32_32x32x16_bf16 v[16:31], v[32:35], v[82:85], v[16:31]
	v_exp_f32_e32 v36, v40
	v_exp_f32_e32 v37, v41
	v_exp_f32_e32 v38, v42
	v_exp_f32_e32 v39, v43
	v_exp_f32_e32 v42, v44
	v_exp_f32_e32 v43, v45
	v_exp_f32_e32 v44, v46
	v_exp_f32_e32 v45, v47
	v_pk_add_f32 v[40:41], v[36:37], v[78:79]
	s_waitcnt lgkmcnt(8)
	v_cvt_pk_bf16_f32 v36, v36, v37
	v_pk_add_f32 v[40:41], v[38:39], v[40:41]
	v_cvt_pk_bf16_f32 v37, v38, v39
	v_pk_add_f32 v[40:41], v[42:43], v[40:41]
	v_cvt_pk_bf16_f32 v38, v42, v43
	v_pk_add_f32 v[46:47], v[44:45], v[40:41]
	v_cvt_pk_bf16_f32 v39, v44, v45
	s_waitcnt lgkmcnt(8)
	v_mfma_f32_32x32x16_bf16 v[48:63], v[74:77], v[66:69], v[48:63]
	v_mfma_f32_32x32x16_bf16 v[16:31], v[36:39], v[94:97], v[16:31]
	s_nop 10
	v_exp_f32_e32 v44, v48
	v_exp_f32_e32 v45, v49
	v_exp_f32_e32 v48, v50
	v_exp_f32_e32 v49, v51
	v_exp_f32_e32 v50, v52
	v_exp_f32_e32 v51, v53
	v_exp_f32_e32 v52, v54
	v_mfma_f32_32x32x16_bf16 v[0:15], v[32:35], v[86:89], v[0:15]
	v_exp_f32_e32 v53, v55
	v_cvt_pk_bf16_f32 v40, v44, v45
	v_pk_add_f32 v[44:45], v[44:45], v[46:47]
	s_waitcnt lgkmcnt(4)
	v_cvt_pk_bf16_f32 v41, v48, v49
	v_pk_add_f32 v[44:45], v[48:49], v[44:45]
	v_cvt_pk_bf16_f32 v42, v50, v51
	v_pk_add_f32 v[44:45], v[50:51], v[44:45]
	v_cvt_pk_bf16_f32 v43, v52, v53
	v_pk_add_f32 v[44:45], v[52:53], v[44:45]
	v_mfma_f32_32x32x16_bf16 v[0:15], v[36:39], v[98:101], v[0:15]
	v_exp_f32_e32 v46, v56
	v_exp_f32_e32 v47, v57
	v_exp_f32_e32 v48, v58
	v_exp_f32_e32 v49, v59
	v_exp_f32_e32 v50, v60
	v_exp_f32_e32 v51, v61
	v_exp_f32_e32 v52, v62
	v_mfma_f32_32x32x16_bf16 v[16:31], v[40:43], v[102:105], v[16:31]
	v_exp_f32_e32 v53, v63
	v_pk_add_f32 v[36:37], v[46:47], v[44:45]
	s_waitcnt lgkmcnt(0)
	v_cvt_pk_bf16_f32 v32, v46, v47
	v_pk_add_f32 v[36:37], v[48:49], v[36:37]
	v_cvt_pk_bf16_f32 v33, v48, v49
	v_pk_add_f32 v[36:37], v[50:51], v[36:37]
	v_mfma_f32_32x32x16_bf16 v[0:15], v[40:43], v[106:109], v[0:15]
	v_cvt_pk_bf16_f32 v34, v50, v51
	v_cvt_pk_bf16_f32 v35, v52, v53
	v_add_f32_e64 v36, v52, v36
	v_add_f32_e64 v37, v53, v37
	v_mfma_f32_32x32x16_bf16 v[16:31], v[32:35], v[122:125], v[16:31]
	v_mfma_f32_32x32x16_bf16 v[0:15], v[32:35], v[126:129], v[0:15]
	v_add_f32_e32 v32, v36, v37
	s_add_i32 s4, s4, 2
	s_addk_i32 s5, 0x4000
	s_cmp_lt_i32 s4, s1
	v_add_f32_e32 v157, v91, v32
	s_cbranch_scc0 .LBB0_208

.LBB0_204:
	s_waitcnt lgkmcnt(3)
	v_mfma_f32_32x32x16_bf16 v[32:47], v[86:89], v[70:73], v[32:47]
	v_add_u32_e32 v139, s8, v152
	ds_read_b64_tr_b16 v[122:123], v139 offset:0
	ds_read_b64_tr_b16 v[124:125], v139 offset:512
	ds_read_b64_tr_b16 v[86:87], v139 offset:4096
	ds_read_b64_tr_b16 v[88:89], v139 offset:4608
	ds_read_b64_tr_b16 v[130:131], v139 offset:1024
	ds_read_b64_tr_b16 v[132:133], v139 offset:1536
	ds_read_b64_tr_b16 v[140:141], v139 offset:5120
	s_waitcnt lgkmcnt(8)
	v_mfma_f32_32x32x16_bf16 v[32:47], v[78:81], v[66:69], v[32:47]
	ds_read_b64_tr_b16 v[142:143], v139 offset:5632
	ds_read_b64_tr_b16 v[134:135], v139 offset:2048
	ds_read_b64_tr_b16 v[136:137], v139 offset:2560
	s_add_i32 s7, s58, 1
	s_cmp_eq_u32 s58, s43
	s_cselect_b32 s7, s42, s7
	s_nop 8
	v_exp_f32_e32 v94, v32
	v_mfma_f32_32x32x16_bf16 v[48:63], v[82:85], v[70:73], v[48:63]
	ds_read_b64_tr_b16 v[82:83], v139 offset:6144
	ds_read_b64_tr_b16 v[84:85], v139 offset:6656
	ds_read_b64_tr_b16 v[158:159], v139 offset:3072
	ds_read_b64_tr_b16 v[160:161], v139 offset:3584
	ds_read_b64_tr_b16 v[162:163], v139 offset:7168
	v_exp_f32_e32 v95, v33
	v_exp_f32_e32 v96, v34
	v_exp_f32_e32 v97, v35
	v_exp_f32_e32 v98, v36
	v_exp_f32_e32 v99, v37
	v_exp_f32_e32 v100, v38
	v_exp_f32_e32 v101, v39
	ds_read_b64_tr_b16 v[164:165], v139 offset:7680
	s_waitcnt lgkmcnt(12)
	v_cvt_pk_bf16_f32 v32, v94, v95
	v_cvt_pk_bf16_f32 v33, v96, v97
	v_cvt_pk_bf16_f32 v34, v98, v99
	v_cvt_pk_bf16_f32 v35, v100, v101
	s_waitcnt lgkmcnt(12)
	v_mfma_f32_32x32x16_bf16 v[48:63], v[74:77], v[66:69], v[48:63]
	v_exp_f32_e32 v102, v40
	v_exp_f32_e32 v103, v41
	v_exp_f32_e32 v104, v42
	v_exp_f32_e32 v105, v43
	v_exp_f32_e32 v106, v44
	v_exp_f32_e32 v107, v45
	v_exp_f32_e32 v108, v46
	v_mfma_f32_32x32x16_bf16 v[16:31], v[32:35], v[122:125], v[16:31]
	v_exp_f32_e32 v109, v47
	s_waitcnt lgkmcnt(8)
	v_cvt_pk_bf16_f32 v36, v102, v103
	v_cvt_pk_bf16_f32 v37, v104, v105
	v_cvt_pk_bf16_f32 v38, v106, v107
	v_cvt_pk_bf16_f32 v39, v108, v109
	s_nop 1
	v_mfma_f32_32x32x16_bf16 v[16:31], v[36:39], v[130:133], v[16:31]
	v_exp_f32_e32 v122, v48
	v_exp_f32_e32 v123, v49
	v_exp_f32_e32 v124, v50
	v_exp_f32_e32 v125, v51
	v_exp_f32_e32 v126, v52
	v_exp_f32_e32 v127, v53
	v_exp_f32_e32 v128, v54
	v_exp_f32_e32 v129, v55
	s_waitcnt lgkmcnt(4)
	v_cvt_pk_bf16_f32 v40, v122, v123
	v_cvt_pk_bf16_f32 v41, v124, v125
	v_cvt_pk_bf16_f32 v42, v126, v127
	v_cvt_pk_bf16_f32 v43, v128, v129
	v_mfma_f32_32x32x16_bf16 v[0:15], v[32:35], v[86:89], v[0:15]
	v_exp_f32_e32 v130, v56
	v_exp_f32_e32 v131, v57
	v_exp_f32_e32 v132, v58
	v_exp_f32_e32 v133, v59
	s_waitcnt lgkmcnt(0)
	v_cvt_pk_bf16_f32 v32, v130, v131
	v_cvt_pk_bf16_f32 v33, v132, v133
	v_mfma_f32_32x32x16_bf16 v[0:15], v[36:39], v[140:143], v[0:15]
	v_mfma_f32_32x32x16_bf16 v[16:31], v[40:43], v[134:137], v[16:31]
	v_exp_f32_e32 v134, v60
	v_exp_f32_e32 v135, v61
	v_exp_f32_e32 v136, v62
	v_exp_f32_e32 v137, v63
	v_cvt_pk_bf16_f32 v34, v134, v135
	v_cvt_pk_bf16_f32 v35, v136, v137
	v_mfma_f32_32x32x16_bf16 v[0:15], v[40:43], v[82:85], v[0:15]
	s_nop 0
	v_mfma_f32_32x32x16_bf16 v[16:31], v[32:35], v[158:161], v[16:31]
	v_mfma_f32_32x32x16_bf16 v[0:15], v[32:35], v[162:165], v[0:15]
	v_lshl_or_b32 v32, s7, 6, v151
	ds_read_b128 v[86:89], v138 offset:8192
	ds_read_b128 v[82:85], v138 offset:8704
	v_cvt_f32_i32_e32 v32, v32
	ds_read_b128 v[78:81], v138 offset:10240
	ds_read_b128 v[74:77], v138 offset:10752
	s_cmp_lg_u32 s7, s67
	s_mov_b64 s[28:29], -1
	v_sub_f32_e32 v138, v32, v155
	s_cbranch_scc0 .LBB0_206
	s_cmp_gt_i32 s7, s67
	s_cselect_b64 s[8:9], -1, 0
	v_cndmask_b32_e64 v36, v120, -v120, s[8:9]
	v_fma_f32 v32, v36, v138, -s0
	s_mov_b32 s8, 2.0
	v_add_f32_e32 v33, v36, v32
	s_mov_b32 s9, 0x40400000
	v_pk_fma_f32 v[34:35], v[36:37], s[8:9], v[32:33] op_sel_hi:[0,1,0]
	v_mul_f32_e32 v46, 0x41000000, v36
	v_mul_f32_e32 v60, 0x42000000, v36
	v_pk_add_f32 v[36:37], v[46:47], v[32:33] op_sel_hi:[0,1]
	v_pk_add_f32 v[38:39], v[46:47], v[34:35] op_sel_hi:[0,1]
	v_pk_add_f32 v[40:41], v[46:47], v[36:37] op_sel_hi:[0,1]
	v_pk_add_f32 v[42:43], v[46:47], v[38:39] op_sel_hi:[0,1]
	v_pk_add_f32 v[44:45], v[46:47], v[40:41] op_sel_hi:[0,1]
	v_pk_add_f32 v[46:47], v[46:47], v[42:43] op_sel_hi:[0,1]
	v_pk_add_f32 v[50:51], v[60:61], v[34:35] op_sel_hi:[0,1]
	v_pk_add_f32 v[54:55], v[60:61], v[38:39] op_sel_hi:[0,1]
	v_pk_add_f32 v[58:59], v[60:61], v[42:43] op_sel_hi:[0,1]
	v_pk_add_f32 v[62:63], v[60:61], v[46:47] op_sel_hi:[0,1]
	v_pk_add_f32 v[48:49], v[60:61], v[32:33] op_sel_hi:[0,1]
	v_pk_add_f32 v[52:53], v[60:61], v[36:37] op_sel_hi:[0,1]
	v_pk_add_f32 v[56:57], v[60:61], v[40:41] op_sel_hi:[0,1]
	v_pk_add_f32 v[60:61], v[60:61], v[44:45] op_sel_hi:[0,1]
	s_mov_b64 s[28:29], 0
